# v50 + NSA selected loop unmasked path: O rescaled/accumulated in place, 16 v_mov_b64 latch copies skipped on that path
# speedup vs baseline: 1.0053x; 1.0033x over previous
; #define MFMA(a, b, c) __builtin_amdgcn_mfma_f32_32x32x16_bf16((a), (b), (c), 0, 0, 0)
; DI float shx(float v, int m) { return __shfl_xor(v, m, 64); }
; template <int DQK, bool MASKED, int MODE, class MF>
; DI void attn_step(const bf16_t* sK, const bf16_t* sVt, const bf16x8 (&qf)[DQK / 16], f32x16& o0, f32x16& o1, float& m, float& l,
;                   float sc, const MF& mf, int lane, f32x16 (&s)[2], float invl, bool lanevalid = true) {
;     ...
; #pragma unroll
;   for (int sub = 0; sub < 2; ++sub)
; #pragma unroll
;     for (int ks = 0; ks < DQK / 16; ++ks) kf[sub][ks] = *(const bf16x8*)(sK + (sub * 32 + pr) * KST + ks * 16 + 8 * h);
;   __builtin_amdgcn_sched_barrier(0);
; #pragma unroll
;   for (int q = 0; q < 16; ++q) { s[0][q] = 0.f; s[1][q] = 0.f; }
; #pragma unroll
;   for (int ks = 0; ks < DQK / 16; ++ks) {
;     s[0] = MFMA(kf[0][ks], qf[ks], s[0]);
;     s[1] = MFMA(kf[1][ks], qf[ks], s[1]);
;   }
;   bf16x8 vf[2][2][2];
;   if (MODE != 1) {
; #pragma unroll
;     for (int sub = 0; sub < 2; ++sub)
; #pragma unroll
;       for (int s2 = 0; s2 < 2; ++s2) {
;         vf[sub][s2][0] = *(const bf16x8*)(sVt + r * 72 + sub * 32 + s2 * 16 + 8 * h);
;         vf[sub][s2][1] = *(const bf16x8*)(sVt + (32 + r) * 72 + sub * 32 + s2 * 16 + 8 * h);
;       }
;     __builtin_amdgcn_sched_barrier(0);
;   }
;   float mxr = -3.0e38f;
; #pragma unroll
;   for (int sub = 0; sub < 2; ++sub)
; #pragma unroll
;     for (int q = 0; q < 16; ++q) {
;       if (MASKED) { const int kk = sub * 32 + 16 * (q >> 3) + 8 * h + (q & 7); s[sub][q] = mf(kk) ? s[sub][q] : -3.0e38f; }
;       if (MODE != 2) mxr = fmaxf(mxr, s[sub][q]);
;     }
;   float alpha = 1.f;
;   if (MODE != 2) {
;     float mx = fmaxf(m, mxr * sc);
;     mx = fmaxf(mx, shx(mx, 32));
; DI void phase_attn_nsa(const Params& P, bf16_t* og, unsigned char* smem, int L, int G) {
;     ...
;         if ((selU >> j) & 1u) {
;           const bool lsel = (sel >> j) & 1u;
;           auto mf = [&](int kk) { return lsel && (key0 + kk <= t); };
;           if (key0 + 63 > t0) attn_step<64, true, 0>(sK + cb * KVB64, sVt + cb * KVB64, qf, o0, o1, m, l, sc, mf, lane, s, 0.f);
;           else attn_step<64, false, 0>(sK + cb * KVB64, sVt + cb * KVB64, qf, o0, o1, m, l, sc, mf, lane, s, 0.f, lsel);
.LBB0_1349:
	s_lshr_b32 s1, s2, s0
	s_bitcmp0_b32 s1, 0
	s_cbranch_scc1 .LBB0_1355
	v_lshrrev_b32_e32 v0, s0, v183
	s_add_i32 s6, s44, 63
	s_mulk_i32 s5, 0x4800
	v_and_b32_e32 v190, 1, v0
	s_mov_b64 s[0:1], -1
	s_cmp_le_u32 s6, s46
	v_max_f32_e32 v188, v141, v141
	v_add_u32_e32 v189, s5, v153
	v_cmp_eq_u32_e32 vcc, 1, v190
	s_cbranch_scc0 .LBB0_1352
	v_add_u32_e32 v0, s5, v182
	ds_read_b128 v[34:37], v0
	ds_read_b128 v[38:41], v0 offset:32
	ds_read_b128 v[106:109], v0 offset:64
	ds_read_b128 v[110:113], v0 offset:96
	ds_read_b128 v[42:45], v0 offset:4608
	ds_read_b128 v[114:117], v0 offset:4640
	ds_read_b128 v[118:121], v0 offset:4672
	ds_read_b128 v[194:197], v0 offset:4704
	s_waitcnt lgkmcnt(7)
	v_mfma_f32_32x32x16_bf16 v[58:73], v[34:37], v[74:77], 0
	v_add3_u32 v0, v189, v175, v138
	v_add3_u32 v34, v189, v177, v138
	s_waitcnt lgkmcnt(3)
	v_mfma_f32_32x32x16_bf16 v[42:57], v[42:45], v[74:77], 0
	v_mfma_f32_32x32x16_bf16 v[58:73], v[38:41], v[78:81], v[58:73]
	s_waitcnt lgkmcnt(2)
	v_mfma_f32_32x32x16_bf16 v[42:57], v[114:117], v[78:81], v[42:57]
	v_mfma_f32_32x32x16_bf16 v[58:73], v[106:109], v[82:85], v[58:73]
	s_waitcnt lgkmcnt(1)
	v_mfma_f32_32x32x16_bf16 v[42:57], v[118:121], v[82:85], v[42:57]
	v_mfma_f32_32x32x16_bf16 v[58:73], v[110:113], v[86:89], v[58:73]
	ds_read_b128 v[198:201], v0 offset:9216
	ds_read_b128 v[126:129], v0 offset:9248
	ds_read_b128 v[130:133], v34 offset:9216
	ds_read_b128 v[122:125], v34 offset:9248
	ds_read_b128 v[118:121], v0 offset:9280
	ds_read_b128 v[110:113], v0 offset:9312
	ds_read_b128 v[114:117], v34 offset:9280
	ds_read_b128 v[106:109], v34 offset:9312
	s_waitcnt lgkmcnt(8)
	v_mfma_f32_32x32x16_bf16 v[42:57], v[194:197], v[86:89], v[42:57]
	s_nop 1
	v_max3_f32 v0, v58, s8, v59
	v_max3_f32 v0, v0, v60, v61
	v_max3_f32 v0, v0, v62, v63
	v_max3_f32 v0, v0, v64, v65
	v_max3_f32 v0, v0, v66, v67
	v_max3_f32 v0, v0, v68, v69
	v_max3_f32 v0, v0, v70, v71
	v_max3_f32 v0, v0, v72, v73
	s_nop 1
	v_max3_f32 v0, v0, v42, v43
	v_max3_f32 v0, v0, v44, v45
	v_max3_f32 v0, v0, v46, v47
	v_max3_f32 v0, v0, v48, v49
	v_max3_f32 v0, v0, v50, v51
	v_max3_f32 v0, v0, v52, v53
	v_max3_f32 v0, v0, v54, v55
	v_max3_f32 v0, v0, v56, v57
	v_mul_f32_e32 v0, 0x3e38aa3b, v0
	v_max_f32_e32 v0, v188, v0
	ds_bpermute_b32 v34, v173, v0
	s_mov_b64 s[0:1], 0
	s_waitcnt lgkmcnt(0)
; #define MFMA(a, b, c) __builtin_amdgcn_mfma_f32_32x32x16_bf16((a), (b), (c), 0, 0, 0)
; DI unsigned pack2(float a, float b) { f32x2_t v = {a, b}; bf16x2_t r = __builtin_convertvector(v, bf16x2_t); return __builtin_bit_cast(unsigned, r); }
; DI float fexp2(float x) { return __builtin_amdgcn_exp2f(x); }
; DI float shx(float v, int m) { return __shfl_xor(v, m, 64); }
; template <int DQK, bool MASKED, int MODE, class MF>
; DI void attn_step(const bf16_t* sK, const bf16_t* sVt, const bf16x8 (&qf)[DQK / 16], f32x16& o0, f32x16& o1, float& m, float& l,
;                   float sc, const MF& mf, int lane, f32x16 (&s)[2], float invl, bool lanevalid = true) {
;     ...
;   float alpha = 1.f;
;   if (MODE != 2) {
;     float mx = fmaxf(m, mxr * sc);
;     mx = fmaxf(mx, shx(mx, 32));
;     if (!MASKED) mx = lanevalid ? mx : m;
;     alpha = fexp2(m - mx);
;     m = mx;
;   }
;   const float moff = (!MASKED && !lanevalid) ? 1.0e30f : m;
;   float ps = 0.f;
; #pragma unroll
;   for (int sub = 0; sub < 2; ++sub)
; #pragma unroll
;     for (int q = 0; q < 16; ++q) {
;       float pv = fexp2(__builtin_fmaf(s[sub][q], sc, -moff));
;       if (MASKED && MODE != 0) pv = (s[sub][q] > -1.0e38f) ? pv : 0.f;
;       if (MODE == 2) pv *= invl;
;       s[sub][q] = pv;
;       ps += pv;
;     }
;   if (MODE != 2) {
;     ps += shx(ps, 32);
;     l = l * alpha + ps;
;   }
;   if (MODE == 1) return;
;   if (MODE == 0) {
; #pragma unroll
;     for (int q = 0; q < 16; ++q) { o0[q] *= alpha; o1[q] *= alpha; }
;   }
; #pragma unroll
;   for (int sub = 0; sub < 2; ++sub)
; #pragma unroll
;     for (int s2 = 0; s2 < 2; ++s2) {
;       union { bf16x8 v; unsigned u[4]; } pb;
; #pragma unroll
;       for (int e = 0; e < 4; ++e) pb.u[e] = pack2(s[sub][8 * s2 + 2 * e], s[sub][8 * s2 + 2 * e + 1]);
;       o0 = MFMA(vf[sub][s2][0], pb.v, o0);
;       o1 = MFMA(vf[sub][s2][1], pb.v, o1);
;     }
	v_max_f32_e32 v34, v34, v34
	v_max_f32_e32 v34, v0, v34
	v_cndmask_b32_e64 v191, v167, -v34, vcc
	v_fmamk_f32 v35, v58, 0x3e38aa3b, v191
	v_fmamk_f32 v36, v59, 0x3e38aa3b, v191
	v_exp_f32_e32 v58, v35
	v_fmamk_f32 v37, v60, 0x3e38aa3b, v191
	v_exp_f32_e32 v59, v36
	v_exp_f32_e32 v60, v37
	v_fmamk_f32 v35, v61, 0x3e38aa3b, v191
	v_exp_f32_e32 v61, v35
	v_add_f32_e32 v36, 0, v58
	v_fmamk_f32 v35, v62, 0x3e38aa3b, v191
	v_add_f32_e32 v36, v59, v36
	v_exp_f32_e32 v62, v35
	v_fmamk_f32 v35, v63, 0x3e38aa3b, v191
	v_add_f32_e32 v36, v60, v36
	v_exp_f32_e32 v63, v35
	v_fmamk_f32 v35, v64, 0x3e38aa3b, v191
	v_exp_f32_e32 v64, v35
	v_add_f32_e32 v35, v61, v36
	v_fmamk_f32 v36, v65, 0x3e38aa3b, v191
	v_exp_f32_e32 v65, v36
	v_fmamk_f32 v36, v66, 0x3e38aa3b, v191
	v_add_f32_e32 v35, v62, v35
	v_exp_f32_e32 v203, v36
	v_fmamk_f32 v36, v67, 0x3e38aa3b, v191
	v_add_f32_e32 v35, v63, v35
	v_exp_f32_e32 v204, v36
	v_fmamk_f32 v36, v68, 0x3e38aa3b, v191
	v_add_f32_e32 v35, v64, v35
	v_exp_f32_e32 v205, v36
	v_fmamk_f32 v36, v69, 0x3e38aa3b, v191
	v_add_f32_e32 v35, v65, v35
	v_exp_f32_e32 v206, v36
	v_fmamk_f32 v36, v70, 0x3e38aa3b, v191
	v_add_f32_e32 v35, v203, v35
	v_exp_f32_e32 v207, v36
	v_fmamk_f32 v36, v71, 0x3e38aa3b, v191
	v_add_f32_e32 v35, v204, v35
	v_exp_f32_e32 v208, v36
	v_fmamk_f32 v36, v72, 0x3e38aa3b, v191
	v_add_f32_e32 v35, v205, v35
	v_exp_f32_e32 v209, v36
	v_fmamk_f32 v36, v73, 0x3e38aa3b, v191
	v_add_f32_e32 v35, v206, v35
	v_exp_f32_e32 v210, v36
	v_fmamk_f32 v36, v42, 0x3e38aa3b, v191
	v_add_f32_e32 v35, v207, v35
	v_exp_f32_e32 v211, v36
	v_fmamk_f32 v36, v43, 0x3e38aa3b, v191
	v_add_f32_e32 v35, v208, v35
	v_exp_f32_e32 v212, v36
	v_fmamk_f32 v36, v44, 0x3e38aa3b, v191
	v_add_f32_e32 v35, v209, v35
	v_exp_f32_e32 v213, v36
	v_fmamk_f32 v36, v45, 0x3e38aa3b, v191
	v_add_f32_e32 v35, v210, v35
	v_exp_f32_e32 v214, v36
	v_fmamk_f32 v36, v46, 0x3e38aa3b, v191
	v_add_f32_e32 v35, v211, v35
	v_exp_f32_e32 v215, v36
	v_fmamk_f32 v36, v47, 0x3e38aa3b, v191
	v_cndmask_b32_e32 v0, v141, v34, vcc
	v_add_f32_e32 v35, v212, v35
	v_exp_f32_e32 v216, v36
	v_fmamk_f32 v36, v48, 0x3e38aa3b, v191
	v_sub_f32_e32 v34, v141, v0
	v_add_f32_e32 v35, v213, v35
	v_exp_f32_e32 v217, v36
	v_add_f32_e32 v35, v214, v35
	v_exp_f32_e32 v202, v34
	v_add_f32_e32 v35, v215, v35
	v_add_f32_e32 v35, v216, v35
	v_add_f32_e32 v218, v217, v35
	v_fmamk_f32 v35, v49, 0x3e38aa3b, v191
	v_fmamk_f32 v34, v50, 0x3e38aa3b, v191
	v_exp_f32_e32 v219, v35
	v_exp_f32_e32 v220, v34
	v_pk_mul_f32 v[32:33], v[32:33], v[202:203] op_sel_hi:[1,0]
	v_pk_mul_f32 v[30:31], v[30:31], v[202:203] op_sel_hi:[1,0]
	v_pk_mul_f32 v[28:29], v[28:29], v[202:203] op_sel_hi:[1,0]
	v_pk_mul_f32 v[26:27], v[26:27], v[202:203] op_sel_hi:[1,0]
	v_pk_mul_f32 v[24:25], v[24:25], v[202:203] op_sel_hi:[1,0]
	v_pk_mul_f32 v[22:23], v[22:23], v[202:203] op_sel_hi:[1,0]
	v_pk_mul_f32 v[20:21], v[20:21], v[202:203] op_sel_hi:[1,0]
	v_pk_mul_f32 v[18:19], v[18:19], v[202:203] op_sel_hi:[1,0]
	v_cvt_pk_bf16_f32 v194, v58, v59
	v_cvt_pk_bf16_f32 v195, v60, v61
	v_cvt_pk_bf16_f32 v196, v62, v63
	v_cvt_pk_bf16_f32 v197, v64, v65
	v_pk_mul_f32 v[16:17], v[16:17], v[202:203] op_sel_hi:[1,0]
	v_pk_mul_f32 v[14:15], v[14:15], v[202:203] op_sel_hi:[1,0]
	v_mfma_f32_32x32x16_bf16 v[18:33], v[198:201], v[194:197], v[18:33]
	v_mul_f32_e64 v12, v12, v202
	v_mul_f32_e64 v13, v13, v202
	v_mul_f32_e64 v10, v10, v202
	v_mul_f32_e64 v11, v11, v202
	v_mul_f32_e64 v8, v8, v202
	v_mul_f32_e64 v9, v9, v202
	v_pk_mul_f32 v[6:7], v[6:7], v[202:203] op_sel_hi:[1,0]
	v_pk_mul_f32 v[4:5], v[4:5], v[202:203] op_sel_hi:[1,0]
	v_pk_mul_f32 v[2:3], v[2:3], v[202:203] op_sel_hi:[1,0]
	v_fmamk_f32 v51, v51, 0x3e38aa3b, v191
	v_add_f32_e32 v50, v219, v218
	v_mfma_f32_32x32x16_bf16 v[2:17], v[130:133], v[194:197], v[2:17]
	v_cvt_pk_bf16_f32 v130, v203, v204
	v_cvt_pk_bf16_f32 v131, v205, v206
	v_cvt_pk_bf16_f32 v132, v207, v208
	v_cvt_pk_bf16_f32 v133, v209, v210
	v_add_f32_e32 v50, v220, v50
	v_fmamk_f32 v55, v55, 0x3e38aa3b, v191
	v_exp_f32_e32 v55, v55
	v_mfma_f32_32x32x16_bf16 v[18:33], v[126:129], v[130:133], v[18:33]
	v_exp_f32_e32 v126, v51
	v_fmamk_f32 v51, v52, 0x3e38aa3b, v191
	v_exp_f32_e32 v127, v51
	v_fmamk_f32 v51, v53, 0x3e38aa3b, v191
	v_exp_f32_e32 v128, v51
	v_add_f32_e32 v50, v126, v50
	v_add_f32_e32 v50, v127, v50
	v_mfma_f32_32x32x16_bf16 v[2:17], v[122:125], v[130:133], v[2:17]
	v_add_f32_e32 v122, v128, v50
	v_fmamk_f32 v50, v54, 0x3e38aa3b, v191
	v_exp_f32_e32 v54, v50
	v_fmamk_f32 v56, v56, 0x3e38aa3b, v191
	v_exp_f32_e32 v56, v56
	v_fmac_f32_e32 v191, 0x3e38aa3b, v57
	v_cvt_pk_bf16_f32 v50, v211, v212
	v_cvt_pk_bf16_f32 v51, v213, v214
	v_cvt_pk_bf16_f32 v52, v215, v216
	v_cvt_pk_bf16_f32 v53, v217, v219
	v_exp_f32_e32 v57, v191
	s_nop 0
	v_mfma_f32_32x32x16_bf16 v[18:33], v[118:121], v[50:53], v[18:33]
	v_add_f32_e32 v118, v54, v122
	v_cvt_pk_bf16_f32 v54, v54, v55
	v_mfma_f32_32x32x16_bf16 v[2:17], v[114:117], v[50:53], v[2:17]
	v_add_f32_e32 v50, v55, v118
	v_add_f32_e32 v50, v56, v50
	v_add_f32_e32 v50, v57, v50
	ds_bpermute_b32 v51, v173, v50
	v_cvt_pk_bf16_f32 v52, v220, v126
	v_cvt_pk_bf16_f32 v53, v127, v128
	v_cvt_pk_bf16_f32 v55, v56, v57
	s_waitcnt lgkmcnt(0)
	v_add_f32_e32 v50, v50, v51
	v_mfma_f32_32x32x16_bf16 v[18:33], v[110:113], v[52:55], v[18:33]
	v_fmac_f32_e32 v50, v185, v202
	v_mfma_f32_32x32x16_bf16 v[2:17], v[106:109], v[52:55], v[2:17]
	s_nop 11
	v_mov_b32_e32 v141, v0
	v_mov_b32_e32 v185, v50
	s_branch .LBB0_1355
